# write-through dwordx4 stores plus nt on the 8 once-read x-row loads of the first phase
# baseline (speedup 1.0000x reference)
; __device__ __forceinline__ float wave_sum(float v) {
; #pragma unroll
;     for (int o = 1; o < 64; o <<= 1) v += __shfl_xor(v, o);
;     return v;
; __device__ __forceinline__ void p0_row(const float* xrow, bf16_t* hbrow, float* ss, int lane) {
;     f32x4 v[8]; float s = 0.f;
; #pragma unroll
;     for (int j = 0; j < 8; ++j) { v[j] = *(const f32x4*)(xrow + 4 * lane + 256 * j); s += (v[j].x * v[j].x + v[j].y * v[j].y) + (v[j].z * v[j].z + v[j].w * v[j].w); }
;     s = wave_sum(s);
;     if (lane < 32) ss[lane] = lane == 0 ? s : 0.f;
.LBB0_543:
	v_add_co_u32_e32 v46, vcc, 0xfffff000, v38
	global_load_dwordx4 v[2:5], v[38:39], off offset:-3072 nt
	global_load_dwordx4 v[6:9], v[38:39], off offset:-2048 nt
	global_load_dwordx4 v[10:13], v[38:39], off offset:-1024 nt
	global_load_dwordx4 v[14:17], v[38:39], off nt
	v_addc_co_u32_e32 v47, vcc, -1, v39, vcc
	global_load_dwordx4 v[30:33], v[46:47], off offset:-3072 nt
	global_load_dwordx4 v[26:29], v[46:47], off offset:-2048 nt
	global_load_dwordx4 v[22:25], v[46:47], off offset:-1024 nt
	global_load_dwordx4 v[18:21], v[38:39], off offset:-4096 nt
	s_waitcnt vmcnt(7)
	v_mul_f32_e32 v1, v3, v3
	v_mul_f32_e32 v46, v5, v5
	s_waitcnt vmcnt(6)
	v_mul_f32_e32 v47, v7, v7
	v_mul_f32_e32 v48, v9, v9
	s_waitcnt vmcnt(5)
	v_mul_f32_e32 v49, v11, v11
	v_mul_f32_e32 v50, v13, v13
	s_waitcnt vmcnt(3)
	v_mul_f32_e32 v53, v31, v31
	v_mul_f32_e32 v54, v33, v33
	s_waitcnt vmcnt(2)
	v_mul_f32_e32 v55, v27, v27
	v_mul_f32_e32 v56, v29, v29
	v_fmac_f32_e32 v1, v2, v2
	v_fmac_f32_e32 v46, v4, v4
	v_fmac_f32_e32 v47, v6, v6
	v_fmac_f32_e32 v48, v8, v8
	v_fmac_f32_e32 v49, v10, v10
	v_fmac_f32_e32 v50, v12, v12
	s_waitcnt vmcnt(1)
	v_mul_f32_e32 v57, v23, v23
	v_mul_f32_e32 v58, v25, v25
	v_fmac_f32_e32 v53, v30, v30
	v_fmac_f32_e32 v54, v32, v32
	v_fmac_f32_e32 v55, v26, v26
	v_fmac_f32_e32 v56, v28, v28
	s_waitcnt vmcnt(0)
	v_mul_f32_e32 v59, v19, v19
	v_mul_f32_e32 v60, v21, v21
	v_add_f32_e32 v1, v1, v46
	v_add_f32_e32 v46, v47, v48
	v_add_f32_e32 v47, v49, v50
	v_fmac_f32_e32 v57, v22, v22
	v_fmac_f32_e32 v58, v24, v24
	v_add_f32_e32 v48, v53, v54
	v_add_f32_e32 v49, v55, v56
	v_fmac_f32_e32 v59, v18, v18
	v_fmac_f32_e32 v60, v20, v20
	v_add_f32_e32 v50, v57, v58
	v_add_f32_e32 v48, v48, v49
	v_add_f32_e32 v53, v59, v60
	v_add_f32_e32 v48, v48, v50
	v_add_f32_e32 v48, v48, v53
	v_mul_f32_e32 v51, v15, v15
	v_mul_f32_e32 v52, v17, v17
	v_add_f32_e32 v1, v48, v1
	v_fmac_f32_e32 v51, v14, v14
	v_fmac_f32_e32 v52, v16, v16
	v_add_f32_e32 v1, v1, v46
	v_add_f32_e32 v1, v1, v47
	v_add_f32_e32 v46, v51, v52
	v_add_f32_e32 v1, v1, v46
	ds_bpermute_b32 v46, v40, v1
	s_waitcnt lgkmcnt(0)
	v_add_f32_e32 v1, v1, v46
	ds_bpermute_b32 v46, v41, v1
	s_waitcnt lgkmcnt(0)
	v_add_f32_e32 v1, v1, v46
	ds_bpermute_b32 v46, v42, v1
	s_waitcnt lgkmcnt(0)
	v_add_f32_e32 v1, v1, v46
	ds_bpermute_b32 v46, v43, v1
	s_waitcnt lgkmcnt(0)
	v_add_f32_e32 v1, v1, v46
	ds_bpermute_b32 v46, v44, v1
	s_waitcnt lgkmcnt(0)
	v_add_f32_e32 v1, v1, v46
	ds_bpermute_b32 v46, v45, v1
	s_and_saveexec_b64 s[16:17], s[4:5]
	s_cbranch_execz .LBB0_542
	s_waitcnt lgkmcnt(0)
	v_add_f32_e32 v1, v1, v46
	v_cndmask_b32_e64 v1, 0, v1, s[6:7]
	v_lshl_add_u64 v[46:47], s[8:9], 0, v[34:35]
	global_store_dword v[46:47], v1, off
	s_branch .LBB0_542
